# placement: attention tile loop moved back to its byte offset mod 64 of the previous best (s_nop padding outside the loop), content = pointer-hoist version
# speedup vs baseline: 1.0024x; 1.0024x over previous
.LBB0_1407:
	v_lshrrev_b32_e32 v33, 2, v152
	v_lshlrev_b32_e32 v32, 5, v59
	v_or_b32_e32 v33, v166, v33
	s_add_i32 s2, 0, 0xc000
	v_and_b32_e32 v32, 32, v32
	v_lshlrev_b32_e32 v33, 6, v33
	v_add_u32_e32 v34, s2, v61
	v_add3_u32 v172, v34, v32, v33
	s_nop 2
	v_max_f32_e32 v32, v16, v16
	v_max_f32_e32 v33, v0, v0
	v_max_f32_e32 v32, v33, v32
	v_max_f32_e32 v33, v17, v17
	v_max_f32_e32 v34, v1, v1
	v_max_f32_e32 v33, v34, v33
	v_max_f32_e32 v34, v19, v19
	v_max_f32_e32 v35, v3, v3
	v_max_f32_e32 v34, v35, v34
	v_max3_f32 v35, v2, v18, v6
	v_max3_f32 v34, v34, v7, v23
	v_max3_f32 v32, v32, v4, v20
	v_max3_f32 v33, v33, v5, v21
	v_max3_f32 v35, v35, v22, v10
	v_max3_f32 v34, v34, v11, v27
	v_max3_f32 v32, v32, v8, v24
	v_max3_f32 v33, v33, v9, v25
	v_max3_f32 v35, v35, v26, v14
	v_max3_f32 v34, v34, v15, v31
	v_max3_f32 v32, v32, v12, v28
	v_max3_f32 v33, v33, v13, v29
	v_max3_f32 v34, v35, v30, v34
	v_max3_f32 v32, v32, v33, v34
	v_mov_b32_e32 v33, v32
	s_nop 1
	v_permlane32_swap_b32_e32 v32, v33
	v_max_f32_e32 v33, v33, v33
	v_max_f32_e32 v32, v32, v32
	v_max_f32_e32 v33, v32, v33
	v_sub_f32_e32 v0, v0, v33
	v_sub_f32_e32 v16, v16, v33
	v_sub_f32_e32 v34, v17, v33
	v_sub_f32_e32 v2, v2, v33
	v_sub_f32_e32 v18, v18, v33
	v_sub_f32_e32 v17, v3, v33
	v_sub_f32_e32 v35, v19, v33
	v_sub_f32_e32 v19, v4, v33
	v_sub_f32_e32 v36, v20, v33
	v_sub_f32_e32 v20, v5, v33
	v_sub_f32_e32 v37, v21, v33
	v_sub_f32_e32 v6, v6, v33
	v_sub_f32_e32 v22, v22, v33
	v_sub_f32_e32 v21, v7, v33
	v_sub_f32_e32 v32, v1, v33
	v_sub_f32_e32 v38, v23, v33
	v_sub_f32_e32 v23, v9, v33
	v_exp_f32_e32 v1, v0
	v_exp_f32_e32 v4, v2
	v_exp_f32_e32 v2, v17
	v_exp_f32_e32 v5, v19
	v_exp_f32_e32 v7, v20
	v_exp_f32_e32 v0, v6
	v_exp_f32_e32 v6, v21
	v_exp_f32_e32 v17, v16
	v_exp_f32_e32 v20, v18
	v_exp_f32_e32 v21, v36
	v_exp_f32_e32 v16, v22
	v_sub_f32_e32 v8, v8, v33
	v_sub_f32_e32 v24, v24, v33
	v_sub_f32_e32 v39, v25, v33
	v_sub_f32_e32 v10, v10, v33
	v_sub_f32_e32 v26, v26, v33
	v_sub_f32_e32 v25, v11, v33
	v_exp_f32_e32 v3, v32
	v_exp_f32_e32 v11, v23
	v_exp_f32_e32 v19, v34
	v_exp_f32_e32 v18, v35
	v_exp_f32_e32 v23, v37
	v_exp_f32_e32 v22, v38
	v_sub_f32_e32 v40, v27, v33
	v_sub_f32_e32 v27, v13, v33
	v_exp_f32_e32 v9, v8
	v_exp_f32_e32 v8, v10
	v_exp_f32_e32 v10, v25
	v_exp_f32_e32 v25, v24
	v_exp_f32_e32 v24, v26
	s_lshl_b32 s4, s66, 2
	v_sub_f32_e32 v12, v12, v33
	v_sub_f32_e32 v28, v28, v33
	v_sub_f32_e32 v41, v29, v33
	v_sub_f32_e32 v14, v14, v33
	v_sub_f32_e32 v30, v30, v33
	v_sub_f32_e32 v29, v15, v33
	v_exp_f32_e32 v15, v27
	v_exp_f32_e32 v27, v39
	v_exp_f32_e32 v26, v40
	s_add_i32 s66, s4, 4
	v_sub_f32_e32 v42, v31, v33
	v_exp_f32_e32 v13, v12
	v_exp_f32_e32 v12, v14
	v_exp_f32_e32 v14, v29
	v_exp_f32_e32 v29, v28
	v_exp_f32_e32 v28, v30
	v_pk_add_f32 v[36:37], v[4:5], v[20:21]
	v_pk_add_f32 v[38:39], v[0:1], v[16:17]
	s_xor_b32 s67, s4, -3
	v_readlane_b32 s4, v254, 39
	v_exp_f32_e32 v31, v41
	v_exp_f32_e32 v30, v42
	v_pk_add_f32 v[34:35], v[2:3], v[18:19]
	v_pk_add_f32 v[36:37], v[36:37], v[38:39]
	v_pk_add_f32 v[38:39], v[6:7], v[22:23]
	s_add_i32 s4, s4, s65
	v_pk_add_f32 v[34:35], v[34:35], v[38:39]
	v_pk_add_f32 v[38:39], v[8:9], v[24:25]
	v_cvt_pk_bf16_f32 v143, v0, v6
	v_add_u32_e32 v0, s4, v161
	s_add_u32 s4, s74, s72
	v_pk_add_f32 v[36:37], v[38:39], v[36:37]
	v_pk_add_f32 v[38:39], v[10:11], v[26:27]
	s_addc_u32 s5, 0, s73
	s_lshl_b32 s7, s33, 7
	v_mov_b32_e32 v147, v153
	v_pk_add_f32 v[34:35], v[38:39], v[34:35]
	v_pk_add_f32 v[38:39], v[12:13], v[28:29]
	s_lshl_b32 s6, s64, 7
	s_and_b32 s7, s7, 0x700
	v_pk_add_f32 v[36:37], v[38:39], v[36:37]
	v_pk_add_f32 v[38:39], v[14:15], v[30:31]
	v_cvt_pk_bf16_f32 v140, v1, v3
	v_sub_u32_e32 v173, v0, v166
	v_lshl_add_u64 v[0:1], s[4:5], 0, v[146:147]
	s_or_b32 s8, s7, s6
	v_readlane_b32 s6, v254, 41
	v_pk_add_f32 v[34:35], v[38:39], v[34:35]
	v_cvt_pk_bf16_f32 v141, v4, v2
	v_lshlrev_b64 v[0:1], 12, v[0:1]
	v_and_b32_e32 v2, 3, v58
	s_add_u32 s6, s6, s8
	v_readlane_b32 s7, v254, 42
	v_pk_add_f32 v[34:35], v[34:35], v[36:37]
	v_lshl_or_b32 v0, v2, 4, v0
	s_addc_u32 s7, s7, 0
	v_pk_add_f32 v[34:35], v[34:35], v[34:35] op_sel:[0,1] op_sel_hi:[1,0]
	v_lshl_add_u64 v[154:155], s[6:7], 0, v[0:1]
	v_lshl_add_u64 v[0:1], s[4:5], 0, v[152:153]
	v_mov_b32_e32 v32, v34
	v_lshlrev_b64 v[2:3], 6, v[0:1]
	v_readlane_b32 s4, v254, 43
	v_lshlrev_b32_e32 v169, 3, v59
	v_permlane32_swap_b32_e32 v34, v32
	v_and_or_b32 v2, v58, 48, v2
	v_readlane_b32 s5, v254, 44
	v_lshlrev_b64 v[0:1], 12, v[0:1]
	v_add_f32_e32 v32, v34, v32
	v_lshl_add_u64 v[156:157], s[4:5], 0, v[2:3]
	v_or_b32_e32 v0, s8, v0
	v_add_lshl_u32 v2, s90, v169, 1
	v_mov_b32_e32 v3, v153
	v_readlane_b32 s4, v254, 45
	v_pk_add_f32 v[150:151], v[32:33], 0 op_sel_hi:[1,0]
	v_cvt_pk_bf16_f32 v138, v13, v15
	v_cvt_pk_bf16_f32 v139, v12, v14
	v_lshl_add_u64 v[0:1], v[0:1], 0, v[2:3]
	v_readlane_b32 s5, v254, 46
	v_mov_b32_e32 v14, v153
	v_mov_b32_e32 v15, v153
	v_and_b32_e32 v167, 63, v58
	v_xor_b32_e32 v32, 0x80000000, v151
	v_cvt_pk_bf16_f32 v142, v5, v7
	v_cvt_pk_bf16_f32 v136, v9, v11
	v_cvt_pk_bf16_f32 v137, v8, v10
	v_cvt_pk_bf16_f32 v132, v17, v19
	v_cvt_pk_bf16_f32 v133, v20, v18
	v_cvt_pk_bf16_f32 v134, v21, v23
	v_cvt_pk_bf16_f32 v135, v16, v22
	v_cvt_pk_bf16_f32 v128, v25, v27
	v_cvt_pk_bf16_f32 v129, v24, v26
	v_cvt_pk_bf16_f32 v130, v29, v31
	v_cvt_pk_bf16_f32 v131, v28, v30
	v_lshl_add_u64 v[158:159], s[4:5], 0, v[0:1]
	v_mov_b32_e32 v0, v153
	v_mov_b32_e32 v1, v153
	v_mov_b32_e32 v2, v153
	v_mov_b32_e32 v4, v153
	v_mov_b32_e32 v5, v153
	v_mov_b32_e32 v6, v153
	v_mov_b32_e32 v7, v153
	v_mov_b32_e32 v8, v153
	v_mov_b32_e32 v9, v153
	v_mov_b32_e32 v10, v153
	v_mov_b32_e32 v11, v153
	v_mov_b32_e32 v12, v153
	v_mov_b32_e32 v13, v153
	v_mov_b64_e32 v[30:31], v[14:15]
	v_lshlrev_b32_e32 v170, 3, v60
	s_mov_b32 s85, 4
	v_cmp_gt_u32_e64 s[2:3], 32, v167
	v_lshl_add_u32 v171, v161, 2, s89
	v_lshl_add_u32 v168, v166, 2, s89
	s_mov_b32 s82, 1
	s_mov_b32 s68, 0
	s_movk_i32 s33, 0x7f
	v_mov_b64_e32 v[28:29], v[12:13]
	v_mov_b64_e32 v[26:27], v[10:11]
	v_mov_b64_e32 v[24:25], v[8:9]
	v_mov_b64_e32 v[22:23], v[6:7]
	v_mov_b64_e32 v[20:21], v[4:5]
	v_mov_b64_e32 v[18:19], v[2:3]
	v_mov_b64_e32 v[16:17], v[0:1]
	v_mov_b32_e32 v33, v32
	v_mov_b32_e32 v34, v32
	v_mov_b32_e32 v35, v32
	v_mov_b32_e32 v36, v32
	v_mov_b32_e32 v37, v32
	v_mov_b32_e32 v38, v32
	v_mov_b32_e32 v39, v32
	v_mov_b32_e32 v40, v32
	v_mov_b32_e32 v41, v32
	v_mov_b32_e32 v42, v32
	v_mov_b32_e32 v43, v32
	v_mov_b32_e32 v44, v32
	v_mov_b32_e32 v45, v32
	v_mov_b32_e32 v46, v32
	v_mov_b32_e32 v47, v32
	s_nop 0
	s_nop 0
	s_nop 0
	s_nop 0
	s_nop 0
	s_nop 0
	s_nop 0
	s_nop 0
	s_nop 0
	s_nop 0
	s_nop 0
	s_nop 0
	s_nop 0

; #define WAIT_BAR(N) do { if constexpr (VAR & 4) asm volatile("s_waitcnt vmcnt(" #N ") lgkmcnt(0)" ::: "memory"); else asm volatile("s_waitcnt vmcnt(" #N ") lgkmcnt(0)\n\ts_barrier" ::: "memory"); } while (0)
; #define DMA_K(t, slot) do { if constexpr ((VAR & 16) != 0) break; __builtin_amdgcn_global_load_lds((const unsigned*)(ksrc + (size_t)TT(t) * 64 * KVW), (LAS unsigned*)(kdst + (slot) * KSLOT), 16, 0, 0); \
;                             __builtin_amdgcn_global_load_lds((const unsigned*)(rsrc + (size_t)TT(t) * 64 * ROPE), (LAS unsigned*)(rdst + (slot) * KSLOT), 16, 0, 0); } while (0)
; #define DMA_V(t, slot) do { if constexpr ((VAR & 16) == 0) __builtin_amdgcn_global_load_lds((const unsigned*)(vsrc + (size_t)TT(t) * 64 * KVW), (LAS unsigned*)(vdst + (slot) * VSLOT), 16, 0, 0); } while (0)
; #define KLOAD(slot) do { const LAS unsigned char* kb_ = kb0 + (slot) * KSLOT; _Pragma("unroll") for (int d0 = 0; d0 < 6; ++d0) { kf[2 * d0] = *(const LAS bf16x8*)(kb_ + d0 * 512); kf[2 * d0 + 1] = *(const LAS bf16x8*)(kb_ + d0 * 512 + 6144); } } while (0)
; #define MASKT(P0_, P1_, t) do { const int kbm_ = TT(t) * 64; if (kbm_ + 63 > qlo) mask_tile(P0_, P1_, qm - kbm_); } while (0)
; #define SHIFT(P0_, P1_, dl_) do { m_reg += (dl_); _Pragma("unroll") for (int r = 0; r < 16; ++r) { P0_[r] -= (dl_); P1_[r] -= (dl_); } _Pragma("unroll") for (int r = 0; r < 16; ++r) negm[r] = -m_reg; } while (0)
; #define PBAR_M(t) do { if ((t) + 3 < NT) { WAIT_BAR(6); } else { WAIT_BAR(0); } } while (0)
; #define PBAR_V(t) do { if ((t) + 3 < NT) { WAIT_BAR(6); } else { WAIT_BAR(0); } } while (0)
; template <int VAR> __device__ __forceinline__ void block(const bf16* Q, const bf16* KVB, const bf16* KR, const float* cosT, bf16* OB, LAS unsigned char* lds, int b, int h, int qb, int t0, int wv, ...
;     ...
;     if (trail) WAIT_BAR(0);
;     DMA_K(3, 3); DMA_V(2, 2);
;     KLOAD(0); QK(px0, px1);
;     PBAR_V(0);
;     MASKT(px0, px1, 0);
;     { float pm; ROWMAX(px0, px1, pm); SHIFT(px0, px1, pm); TILE_VALU(1.f); pa0 = pn0; pa1 = pn1; pa2 = pn2; pa3 = pn3; }
;     int sk = 1, sv = 0;
; #pragma unroll 1
;     for (int t = 1; t < NT; ++t) {
;         PBAR_M(t);
.Lat_mbar0:
	s_waitcnt vmcnt(0) lgkmcnt(0)
	s_barrier
	s_branch .Lat_mreads
	s_nop 0
	s_nop 0
	s_nop 0
